# s_setprio 2 for the solve waves (0-3) during chunk-prep step 5, reset at the join
# speedup vs baseline: 1.0018x; 1.0018x over previous
.LBB0_216:
	s_and_b64 vcc, exec, s[28:29]
	s_cbranch_vccz .LBB0_236
	s_setprio 2
	v_lshlrev_b32_e32 v3, 2, v1
	v_ashrrev_i32_e32 v33, 7, v1
	s_movk_i32 s6, 0x2080
	v_and_b32_e32 v32, 12, v3
	v_ashrrev_i32_e32 v14, 2, v1
	v_mul_lo_u32 v2, v33, s6
	v_lshlrev_b32_e32 v19, 2, v32
	v_readlane_b32 s6, v253, 51
	v_and_b32_e32 v15, 31, v14
	v_cmp_eq_u32_e32 vcc, v32, v15
	v_add3_u32 v6, s6, v2, v19
	v_mov_b32_e32 v7, v6
	v_cndmask_b32_e64 v12, 0, 1.0, vcc
	v_or_b32_e32 v31, 1, v32
	v_cmp_eq_u32_e32 vcc, v31, v15
	v_or_b32_e32 v30, 2, v32
	ds_read_b128 v[2:5], v7
	ds_read_b128 v[8:11], v7 offset:64
	v_add_u32_e32 v7, 0x100, v6
	v_cndmask_b32_e64 v13, 0, 1.0, vcc
	v_cmp_eq_u32_e32 vcc, v30, v15
	v_or_b32_e32 v29, 3, v32
	v_or_b32_e32 v28, 16, v32
	v_cndmask_b32_e64 v16, 0, 1.0, vcc
	v_cmp_eq_u32_e32 vcc, v29, v15
	s_waitcnt vmcnt(1)
	ds_read_b128 v[98:101], v7
	ds_read_b128 v[102:105], v7 offset:64
	v_add_u32_e32 v7, 0x200, v6
	v_cndmask_b32_e64 v17, 0, 1.0, vcc
	v_cmp_eq_u32_e32 vcc, v28, v15
	v_or_b32_e32 v27, 17, v32
	v_or_b32_e32 v26, 18, v32
	v_cndmask_b32_e64 v22, 0, 1.0, vcc
	v_cmp_eq_u32_e32 vcc, v27, v15
	ds_read_b128 v[106:109], v7
	ds_read_b128 v[110:113], v7 offset:64
	v_mov_b32_e32 v7, v12
	v_cndmask_b32_e64 v23, 0, 1.0, vcc
	v_cmp_eq_u32_e32 vcc, v26, v15
	v_or_b32_e32 v21, 19, v32
	v_mov_b32_e32 v18, v131
	v_cndmask_b32_e64 v114, 0, 1.0, vcc
	v_cmp_eq_u32_e32 vcc, v21, v15
	v_mov_b32_dpp v18, v7 quad_perm:[0,0,0,0] row_mask:0xf bank_mask:0xf
	v_add_u32_e32 v7, 0x300, v6
	v_cndmask_b32_e64 v115, 0, 1.0, vcc
	s_waitcnt lgkmcnt(5)
	v_pk_fma_f32 v[12:13], v[2:3], v[18:19], v[12:13] op_sel_hi:[1,0,1] neg_lo:[0,1,0] neg_hi:[0,1,0]
	v_pk_fma_f32 v[16:17], v[4:5], v[18:19], v[16:17] op_sel_hi:[1,0,1] neg_lo:[0,1,0] neg_hi:[0,1,0]
	s_waitcnt lgkmcnt(4)
	v_pk_fma_f32 v[22:23], v[8:9], v[18:19], v[22:23] op_sel_hi:[1,0,1] neg_lo:[0,1,0] neg_hi:[0,1,0]
	v_pk_fma_f32 v[114:115], v[10:11], v[18:19], v[114:115] op_sel_hi:[1,0,1] neg_lo:[0,1,0] neg_hi:[0,1,0]
	ds_read_b128 v[2:5], v7
	ds_read_b128 v[8:11], v7 offset:64
	v_mov_b32_e32 v7, v13
	v_mov_b32_e32 v18, v131
	v_mov_b32_e32 v20, v131
	v_readlane_b32 s6, v253, 52
	v_mov_b32_dpp v18, v7 quad_perm:[0,0,0,0] row_mask:0xf bank_mask:0xf
	v_add_u32_e32 v7, 0x400, v6
	s_waitcnt lgkmcnt(5)
	v_pk_fma_f32 v[16:17], v[100:101], v[18:19], v[16:17] op_sel_hi:[1,0,1] neg_lo:[0,1,0] neg_hi:[0,1,0]
	v_pk_fma_f32 v[12:13], v[98:99], v[18:19], v[12:13] op_sel_hi:[1,0,1] neg_lo:[0,1,0] neg_hi:[0,1,0]
	s_waitcnt lgkmcnt(4)
	v_pk_fma_f32 v[114:115], v[104:105], v[18:19], v[114:115] op_sel_hi:[1,0,1] neg_lo:[0,1,0] neg_hi:[0,1,0]
	v_pk_fma_f32 v[22:23], v[102:103], v[18:19], v[22:23] op_sel_hi:[1,0,1] neg_lo:[0,1,0] neg_hi:[0,1,0]
	ds_read_b128 v[98:101], v7
	ds_read_b128 v[102:105], v7 offset:64
	v_mov_b32_e32 v7, v16
	v_mov_b32_e32 v18, v131
	s_movk_i32 s8, 0x48
	v_cmp_eq_u32_e32 vcc, 1, v33
	v_mov_b32_dpp v18, v7 quad_perm:[0,0,0,0] row_mask:0xf bank_mask:0xf
	v_add_u32_e32 v7, 0x500, v6
	s_waitcnt lgkmcnt(5)
	v_pk_fma_f32 v[16:17], v[108:109], v[18:19], v[16:17] op_sel_hi:[1,0,1] neg_lo:[0,1,0] neg_hi:[0,1,0]
	v_pk_fma_f32 v[12:13], v[106:107], v[18:19], v[12:13] op_sel_hi:[1,0,1] neg_lo:[0,1,0] neg_hi:[0,1,0]
	s_waitcnt lgkmcnt(4)
	v_pk_fma_f32 v[114:115], v[112:113], v[18:19], v[114:115] op_sel_hi:[1,0,1] neg_lo:[0,1,0] neg_hi:[0,1,0]
	v_pk_fma_f32 v[22:23], v[110:111], v[18:19], v[22:23] op_sel_hi:[1,0,1] neg_lo:[0,1,0] neg_hi:[0,1,0]
	ds_read_b128 v[106:109], v7
	ds_read_b128 v[110:113], v7 offset:64
	v_mov_b32_e32 v7, v17
	v_mov_b32_e32 v18, v131
	s_nop 1
	v_mov_b32_dpp v18, v7 quad_perm:[0,0,0,0] row_mask:0xf bank_mask:0xf
	v_add_u32_e32 v7, 0x600, v6
	s_waitcnt lgkmcnt(5)
	v_pk_fma_f32 v[12:13], v[2:3], v[18:19], v[12:13] op_sel_hi:[1,0,1] neg_lo:[0,1,0] neg_hi:[0,1,0]
	v_pk_fma_f32 v[16:17], v[4:5], v[18:19], v[16:17] op_sel_hi:[1,0,1] neg_lo:[0,1,0] neg_hi:[0,1,0]
	s_waitcnt lgkmcnt(4)
	v_pk_fma_f32 v[114:115], v[10:11], v[18:19], v[114:115] op_sel_hi:[1,0,1] neg_lo:[0,1,0] neg_hi:[0,1,0]
	v_pk_fma_f32 v[22:23], v[8:9], v[18:19], v[22:23] op_sel_hi:[1,0,1] neg_lo:[0,1,0] neg_hi:[0,1,0]
	ds_read_b128 v[2:5], v7
	ds_read_b128 v[8:11], v7 offset:64
	v_mov_b32_e32 v7, v12
	v_mov_b32_e32 v18, v131
	s_nop 1
	v_mov_b32_dpp v18, v7 quad_perm:[1,1,1,1] row_mask:0xf bank_mask:0xf
	v_add_u32_e32 v7, 0x700, v6
	s_waitcnt lgkmcnt(5)
	v_pk_fma_f32 v[12:13], v[98:99], v[18:19], v[12:13] op_sel_hi:[1,0,1] neg_lo:[0,1,0] neg_hi:[0,1,0]
	v_pk_fma_f32 v[16:17], v[100:101], v[18:19], v[16:17] op_sel_hi:[1,0,1] neg_lo:[0,1,0] neg_hi:[0,1,0]
	s_waitcnt lgkmcnt(4)
	v_pk_fma_f32 v[22:23], v[102:103], v[18:19], v[22:23] op_sel_hi:[1,0,1] neg_lo:[0,1,0] neg_hi:[0,1,0]
	v_pk_fma_f32 v[114:115], v[104:105], v[18:19], v[114:115] op_sel_hi:[1,0,1] neg_lo:[0,1,0] neg_hi:[0,1,0]
	ds_read_b128 v[98:101], v7
	ds_read_b128 v[102:105], v7 offset:64
	v_mov_b32_e32 v7, v13
	v_mov_b32_e32 v18, v131
	s_nop 1
	v_mov_b32_dpp v18, v7 quad_perm:[1,1,1,1] row_mask:0xf bank_mask:0xf
	v_add_u32_e32 v7, 0x800, v6
	s_waitcnt lgkmcnt(5)
	v_pk_fma_f32 v[16:17], v[108:109], v[18:19], v[16:17] op_sel_hi:[1,0,1] neg_lo:[0,1,0] neg_hi:[0,1,0]
	v_pk_fma_f32 v[12:13], v[106:107], v[18:19], v[12:13] op_sel_hi:[1,0,1] neg_lo:[0,1,0] neg_hi:[0,1,0]
	s_waitcnt lgkmcnt(4)
	v_pk_fma_f32 v[114:115], v[112:113], v[18:19], v[114:115] op_sel_hi:[1,0,1] neg_lo:[0,1,0] neg_hi:[0,1,0]
	v_pk_fma_f32 v[22:23], v[110:111], v[18:19], v[22:23] op_sel_hi:[1,0,1] neg_lo:[0,1,0] neg_hi:[0,1,0]
	ds_read_b128 v[106:109], v7
	ds_read_b128 v[110:113], v7 offset:64
	v_mov_b32_e32 v7, v16
	v_mov_b32_e32 v18, v131
	s_nop 1
	v_mov_b32_dpp v18, v7 quad_perm:[1,1,1,1] row_mask:0xf bank_mask:0xf
	v_add_u32_e32 v7, 0x900, v6
	s_waitcnt lgkmcnt(5)
	v_pk_fma_f32 v[16:17], v[4:5], v[18:19], v[16:17] op_sel_hi:[1,0,1] neg_lo:[0,1,0] neg_hi:[0,1,0]
	v_pk_fma_f32 v[12:13], v[2:3], v[18:19], v[12:13] op_sel_hi:[1,0,1] neg_lo:[0,1,0] neg_hi:[0,1,0]
	s_waitcnt lgkmcnt(4)
	v_pk_fma_f32 v[22:23], v[8:9], v[18:19], v[22:23] op_sel_hi:[1,0,1] neg_lo:[0,1,0] neg_hi:[0,1,0]
	v_pk_fma_f32 v[114:115], v[10:11], v[18:19], v[114:115] op_sel_hi:[1,0,1] neg_lo:[0,1,0] neg_hi:[0,1,0]
	ds_read_b128 v[2:5], v7
	ds_read_b128 v[8:11], v7 offset:64
	v_mov_b32_e32 v7, v17
	v_mov_b32_e32 v18, v131
	s_nop 1
	v_mov_b32_dpp v18, v7 quad_perm:[1,1,1,1] row_mask:0xf bank_mask:0xf
	v_add_u32_e32 v7, 0xa00, v6
	s_waitcnt lgkmcnt(5)
	v_pk_fma_f32 v[12:13], v[98:99], v[18:19], v[12:13] op_sel_hi:[1,0,1] neg_lo:[0,1,0] neg_hi:[0,1,0]
	v_pk_fma_f32 v[16:17], v[100:101], v[18:19], v[16:17] op_sel_hi:[1,0,1] neg_lo:[0,1,0] neg_hi:[0,1,0]
	s_waitcnt lgkmcnt(4)
	v_pk_fma_f32 v[114:115], v[104:105], v[18:19], v[114:115] op_sel_hi:[1,0,1] neg_lo:[0,1,0] neg_hi:[0,1,0]
	v_pk_fma_f32 v[22:23], v[102:103], v[18:19], v[22:23] op_sel_hi:[1,0,1] neg_lo:[0,1,0] neg_hi:[0,1,0]
	ds_read_b128 v[98:101], v7
	ds_read_b128 v[102:105], v7 offset:64
	v_mov_b32_e32 v7, v12
	v_mov_b32_e32 v18, v131
	s_nop 1
	v_mov_b32_dpp v18, v7 quad_perm:[2,2,2,2] row_mask:0xf bank_mask:0xf
	v_add_u32_e32 v7, 0xb00, v6
	s_waitcnt lgkmcnt(5)
	v_pk_fma_f32 v[12:13], v[106:107], v[18:19], v[12:13] op_sel_hi:[1,0,1] neg_lo:[0,1,0] neg_hi:[0,1,0]
	v_pk_fma_f32 v[16:17], v[108:109], v[18:19], v[16:17] op_sel_hi:[1,0,1] neg_lo:[0,1,0] neg_hi:[0,1,0]
	s_waitcnt lgkmcnt(4)
	v_pk_fma_f32 v[22:23], v[110:111], v[18:19], v[22:23] op_sel_hi:[1,0,1] neg_lo:[0,1,0] neg_hi:[0,1,0]
	v_pk_fma_f32 v[114:115], v[112:113], v[18:19], v[114:115] op_sel_hi:[1,0,1] neg_lo:[0,1,0] neg_hi:[0,1,0]
	ds_read_b128 v[106:109], v7
	ds_read_b128 v[110:113], v7 offset:64
	v_mov_b32_e32 v7, v13
	v_mov_b32_e32 v18, v131
	s_nop 1
	v_mov_b32_dpp v18, v7 quad_perm:[2,2,2,2] row_mask:0xf bank_mask:0xf
	v_add_u32_e32 v7, 0xc00, v6
	s_waitcnt lgkmcnt(5)
	v_pk_fma_f32 v[16:17], v[4:5], v[18:19], v[16:17] op_sel_hi:[1,0,1] neg_lo:[0,1,0] neg_hi:[0,1,0]
	v_pk_fma_f32 v[12:13], v[2:3], v[18:19], v[12:13] op_sel_hi:[1,0,1] neg_lo:[0,1,0] neg_hi:[0,1,0]
	s_waitcnt lgkmcnt(4)
	v_pk_fma_f32 v[114:115], v[10:11], v[18:19], v[114:115] op_sel_hi:[1,0,1] neg_lo:[0,1,0] neg_hi:[0,1,0]
	v_pk_fma_f32 v[22:23], v[8:9], v[18:19], v[22:23] op_sel_hi:[1,0,1] neg_lo:[0,1,0] neg_hi:[0,1,0]
	ds_read_b128 v[2:5], v7
	ds_read_b128 v[8:11], v7 offset:64
	v_mov_b32_e32 v7, v16
	v_mov_b32_e32 v18, v131
	s_nop 1
	v_mov_b32_dpp v18, v7 quad_perm:[2,2,2,2] row_mask:0xf bank_mask:0xf
	v_add_u32_e32 v7, 0xd00, v6
	s_waitcnt lgkmcnt(5)
	v_pk_fma_f32 v[16:17], v[100:101], v[18:19], v[16:17] op_sel_hi:[1,0,1] neg_lo:[0,1,0] neg_hi:[0,1,0]
	v_pk_fma_f32 v[12:13], v[98:99], v[18:19], v[12:13] op_sel_hi:[1,0,1] neg_lo:[0,1,0] neg_hi:[0,1,0]
	s_waitcnt lgkmcnt(4)
	v_pk_fma_f32 v[22:23], v[102:103], v[18:19], v[22:23] op_sel_hi:[1,0,1] neg_lo:[0,1,0] neg_hi:[0,1,0]
	v_pk_fma_f32 v[114:115], v[104:105], v[18:19], v[114:115] op_sel_hi:[1,0,1] neg_lo:[0,1,0] neg_hi:[0,1,0]
	ds_read_b128 v[98:101], v7
	ds_read_b128 v[102:105], v7 offset:64
	v_mov_b32_e32 v7, v17
	v_mov_b32_e32 v18, v131
	s_nop 1
	v_mov_b32_dpp v18, v7 quad_perm:[2,2,2,2] row_mask:0xf bank_mask:0xf
	v_add_u32_e32 v7, 0xe00, v6
	s_waitcnt lgkmcnt(5)
	v_pk_fma_f32 v[12:13], v[106:107], v[18:19], v[12:13] op_sel_hi:[1,0,1] neg_lo:[0,1,0] neg_hi:[0,1,0]
	v_pk_fma_f32 v[16:17], v[108:109], v[18:19], v[16:17] op_sel_hi:[1,0,1] neg_lo:[0,1,0] neg_hi:[0,1,0]
	s_waitcnt lgkmcnt(4)
	v_pk_fma_f32 v[114:115], v[112:113], v[18:19], v[114:115] op_sel_hi:[1,0,1] neg_lo:[0,1,0] neg_hi:[0,1,0]
	v_pk_fma_f32 v[22:23], v[110:111], v[18:19], v[22:23] op_sel_hi:[1,0,1] neg_lo:[0,1,0] neg_hi:[0,1,0]
	ds_read_b128 v[106:109], v7
	ds_read_b128 v[110:113], v7 offset:64
	v_mov_b32_e32 v7, v12
	v_mov_b32_e32 v18, v131
	s_nop 1
	v_mov_b32_dpp v18, v7 quad_perm:[3,3,3,3] row_mask:0xf bank_mask:0xf
	v_add_u32_e32 v7, 0xf00, v6
	s_waitcnt lgkmcnt(5)
	v_pk_fma_f32 v[12:13], v[2:3], v[18:19], v[12:13] op_sel_hi:[1,0,1] neg_lo:[0,1,0] neg_hi:[0,1,0]
	v_pk_fma_f32 v[16:17], v[4:5], v[18:19], v[16:17] op_sel_hi:[1,0,1] neg_lo:[0,1,0] neg_hi:[0,1,0]
	s_waitcnt lgkmcnt(4)
	v_pk_fma_f32 v[22:23], v[8:9], v[18:19], v[22:23] op_sel_hi:[1,0,1] neg_lo:[0,1,0] neg_hi:[0,1,0]
	v_pk_fma_f32 v[114:115], v[10:11], v[18:19], v[114:115] op_sel_hi:[1,0,1] neg_lo:[0,1,0] neg_hi:[0,1,0]
	ds_read_b128 v[2:5], v7
	ds_read_b128 v[8:11], v7 offset:64
	v_mov_b32_e32 v7, v13
	v_mov_b32_e32 v18, v131
	s_nop 1
	v_mov_b32_dpp v18, v7 quad_perm:[3,3,3,3] row_mask:0xf bank_mask:0xf
	v_add_u32_e32 v7, 0x1000, v6
	s_waitcnt lgkmcnt(5)
	v_pk_fma_f32 v[16:17], v[100:101], v[18:19], v[16:17] op_sel_hi:[1,0,1] neg_lo:[0,1,0] neg_hi:[0,1,0]
	v_pk_fma_f32 v[12:13], v[98:99], v[18:19], v[12:13] op_sel_hi:[1,0,1] neg_lo:[0,1,0] neg_hi:[0,1,0]
	s_waitcnt lgkmcnt(4)
	v_pk_fma_f32 v[104:105], v[104:105], v[18:19], v[114:115] op_sel_hi:[1,0,1] neg_lo:[0,1,0] neg_hi:[0,1,0]
	ds_read_b128 v[98:101], v7 offset:64
	v_mov_b32_e32 v7, v16
	v_pk_fma_f32 v[22:23], v[102:103], v[18:19], v[22:23] op_sel_hi:[1,0,1] neg_lo:[0,1,0] neg_hi:[0,1,0]
	v_mov_b32_e32 v18, v131
	s_nop 1
	v_mov_b32_dpp v18, v7 quad_perm:[3,3,3,3] row_mask:0xf bank_mask:0xf
	v_add_u32_e32 v7, 0x1100, v6
	s_waitcnt lgkmcnt(4)
	v_pk_fma_f32 v[16:17], v[108:109], v[18:19], v[16:17] op_sel_hi:[1,0,1] neg_lo:[0,1,0] neg_hi:[0,1,0]
	v_pk_fma_f32 v[114:115], v[106:107], v[18:19], v[12:13] op_sel_hi:[1,0,1] neg_lo:[0,1,0] neg_hi:[0,1,0]
	s_waitcnt lgkmcnt(3)
	v_pk_fma_f32 v[12:13], v[110:111], v[18:19], v[22:23] op_sel_hi:[1,0,1] neg_lo:[0,1,0] neg_hi:[0,1,0]
	v_pk_fma_f32 v[22:23], v[112:113], v[18:19], v[104:105] op_sel_hi:[1,0,1] neg_lo:[0,1,0] neg_hi:[0,1,0]
	ds_read_b128 v[102:105], v7 offset:64
	v_mov_b32_e32 v7, v17
	v_mov_b32_e32 v18, v131
	s_nop 1
	v_mov_b32_dpp v18, v7 quad_perm:[3,3,3,3] row_mask:0xf bank_mask:0xf
	v_add_u32_e32 v7, 0x1200, v6
	s_waitcnt lgkmcnt(2)
	v_pk_fma_f32 v[12:13], v[8:9], v[18:19], v[12:13] op_sel_hi:[1,0,1] neg_lo:[0,1,0] neg_hi:[0,1,0]
	v_pk_fma_f32 v[22:23], v[10:11], v[18:19], v[22:23] op_sel_hi:[1,0,1] neg_lo:[0,1,0] neg_hi:[0,1,0]
	ds_read_b128 v[8:11], v7 offset:64
	v_mov_b32_e32 v7, v12
	v_pk_fma_f32 v[2:3], v[2:3], v[18:19], v[114:115] op_sel_hi:[1,0,1] neg_lo:[0,1,0] neg_hi:[0,1,0]
	s_nop 0
	v_mov_b32_dpp v20, v7 quad_perm:[0,0,0,0] row_mask:0xf bank_mask:0xf
	v_add_u32_e32 v7, 0x1300, v6
	s_waitcnt lgkmcnt(2)
	v_pk_fma_f32 v[12:13], v[98:99], v[20:21], v[12:13] op_sel_hi:[1,0,1] neg_lo:[0,1,0] neg_hi:[0,1,0]
	v_pk_fma_f32 v[22:23], v[100:101], v[20:21], v[22:23] op_sel_hi:[1,0,1] neg_lo:[0,1,0] neg_hi:[0,1,0]
	ds_read_b128 v[98:101], v7 offset:64
	v_mov_b32_e32 v7, v13
	v_mov_b32_e32 v20, v131
	s_nop 1
	v_mov_b32_dpp v20, v7 quad_perm:[0,0,0,0] row_mask:0xf bank_mask:0xf
	v_add_u32_e32 v7, 0x1400, v6
	s_waitcnt lgkmcnt(2)
	v_pk_fma_f32 v[22:23], v[104:105], v[20:21], v[22:23] op_sel_hi:[1,0,1] neg_lo:[0,1,0] neg_hi:[0,1,0]
	v_pk_fma_f32 v[12:13], v[102:103], v[20:21], v[12:13] op_sel_hi:[1,0,1] neg_lo:[0,1,0] neg_hi:[0,1,0]
	v_mov_b32_e32 v20, v131
	ds_read_b128 v[102:105], v7 offset:64
	v_mov_b32_e32 v7, v22
	s_nop 1
	v_mov_b32_dpp v20, v7 quad_perm:[0,0,0,0] row_mask:0xf bank_mask:0xf
	v_add_u32_e32 v7, 0x1500, v6
	s_waitcnt lgkmcnt(2)
	v_pk_fma_f32 v[22:23], v[10:11], v[20:21], v[22:23] op_sel_hi:[1,0,1] neg_lo:[0,1,0] neg_hi:[0,1,0]
	v_pk_fma_f32 v[12:13], v[8:9], v[20:21], v[12:13] op_sel_hi:[1,0,1] neg_lo:[0,1,0] neg_hi:[0,1,0]
	v_mov_b32_e32 v20, v131
	ds_read_b128 v[8:11], v7 offset:64
	v_mov_b32_e32 v7, v23
	s_nop 1
	v_mov_b32_dpp v20, v7 quad_perm:[0,0,0,0] row_mask:0xf bank_mask:0xf
	v_add_u32_e32 v7, 0x1600, v6
	s_waitcnt lgkmcnt(2)
	v_pk_fma_f32 v[12:13], v[98:99], v[20:21], v[12:13] op_sel_hi:[1,0,1] neg_lo:[0,1,0] neg_hi:[0,1,0]
	v_pk_fma_f32 v[22:23], v[100:101], v[20:21], v[22:23] op_sel_hi:[1,0,1] neg_lo:[0,1,0] neg_hi:[0,1,0]
	ds_read_b128 v[98:101], v7 offset:64
	v_mov_b32_e32 v7, v12
	v_mov_b32_e32 v20, v131
	s_nop 1
	v_mov_b32_dpp v20, v7 quad_perm:[1,1,1,1] row_mask:0xf bank_mask:0xf
	v_add_u32_e32 v7, 0x1700, v6
	s_waitcnt lgkmcnt(2)
	v_pk_fma_f32 v[12:13], v[102:103], v[20:21], v[12:13] op_sel_hi:[1,0,1] neg_lo:[0,1,0] neg_hi:[0,1,0]
	v_pk_fma_f32 v[22:23], v[104:105], v[20:21], v[22:23] op_sel_hi:[1,0,1] neg_lo:[0,1,0] neg_hi:[0,1,0]
	ds_read_b128 v[102:105], v7 offset:64
	v_mov_b32_e32 v7, v13
	v_mov_b32_e32 v20, v131
	s_nop 1
	v_mov_b32_dpp v20, v7 quad_perm:[1,1,1,1] row_mask:0xf bank_mask:0xf
	v_add_u32_e32 v7, 0x1800, v6
	s_waitcnt lgkmcnt(2)
	v_pk_fma_f32 v[22:23], v[10:11], v[20:21], v[22:23] op_sel_hi:[1,0,1] neg_lo:[0,1,0] neg_hi:[0,1,0]
	v_pk_fma_f32 v[12:13], v[8:9], v[20:21], v[12:13] op_sel_hi:[1,0,1] neg_lo:[0,1,0] neg_hi:[0,1,0]
	v_mov_b32_e32 v20, v131
	ds_read_b128 v[8:11], v7 offset:64
	v_mov_b32_e32 v7, v22
	s_nop 1
	v_mov_b32_dpp v20, v7 quad_perm:[1,1,1,1] row_mask:0xf bank_mask:0xf
	v_add_u32_e32 v7, 0x1900, v6
	s_waitcnt lgkmcnt(2)
	v_pk_fma_f32 v[22:23], v[100:101], v[20:21], v[22:23] op_sel_hi:[1,0,1] neg_lo:[0,1,0] neg_hi:[0,1,0]
	v_pk_fma_f32 v[12:13], v[98:99], v[20:21], v[12:13] op_sel_hi:[1,0,1] neg_lo:[0,1,0] neg_hi:[0,1,0]
	v_mov_b32_e32 v20, v131
	ds_read_b128 v[98:101], v7 offset:64
	v_mov_b32_e32 v7, v23
	s_nop 1
	v_mov_b32_dpp v20, v7 quad_perm:[1,1,1,1] row_mask:0xf bank_mask:0xf
	v_add_u32_e32 v7, 0x1a00, v6
	s_waitcnt lgkmcnt(2)
	v_pk_fma_f32 v[12:13], v[102:103], v[20:21], v[12:13] op_sel_hi:[1,0,1] neg_lo:[0,1,0] neg_hi:[0,1,0]
	v_pk_fma_f32 v[22:23], v[104:105], v[20:21], v[22:23] op_sel_hi:[1,0,1] neg_lo:[0,1,0] neg_hi:[0,1,0]
	ds_read_b128 v[102:105], v7 offset:64
	v_mov_b32_e32 v7, v12
	v_mov_b32_e32 v20, v131
	s_nop 1
	v_mov_b32_dpp v20, v7 quad_perm:[2,2,2,2] row_mask:0xf bank_mask:0xf
	v_add_u32_e32 v7, 0x1b00, v6
	s_waitcnt lgkmcnt(2)
	v_pk_fma_f32 v[8:9], v[8:9], v[20:21], v[12:13] op_sel_hi:[1,0,1] neg_lo:[0,1,0] neg_hi:[0,1,0]
	v_mov_b32_e32 v12, v131
	ds_read_b128 v[106:109], v7 offset:64
	v_mov_b32_e32 v7, v9
	v_pk_fma_f32 v[10:11], v[10:11], v[20:21], v[22:23] op_sel_hi:[1,0,1] neg_lo:[0,1,0] neg_hi:[0,1,0]
	v_mov_b32_e32 v20, v131
	v_mov_b32_dpp v12, v7 quad_perm:[2,2,2,2] row_mask:0xf bank_mask:0xf
	v_add_u32_e32 v7, 0x1c00, v6
	s_waitcnt lgkmcnt(2)
	v_pk_fma_f32 v[10:11], v[100:101], v[12:13], v[10:11] op_sel_hi:[1,0,1] neg_lo:[0,1,0] neg_hi:[0,1,0]
	v_pk_fma_f32 v[8:9], v[98:99], v[12:13], v[8:9] op_sel_hi:[1,0,1] neg_lo:[0,1,0] neg_hi:[0,1,0]
	v_mov_b32_e32 v12, v131
	ds_read_b128 v[98:101], v7 offset:64
	v_mov_b32_e32 v7, v10
	s_nop 1
	v_mov_b32_dpp v12, v7 quad_perm:[2,2,2,2] row_mask:0xf bank_mask:0xf
	v_add_u32_e32 v7, 0x1d00, v6
	s_waitcnt lgkmcnt(2)
	v_pk_fma_f32 v[22:23], v[104:105], v[12:13], v[10:11] op_sel_hi:[1,0,1] neg_lo:[0,1,0] neg_hi:[0,1,0]
	v_pk_fma_f32 v[8:9], v[102:103], v[12:13], v[8:9] op_sel_hi:[1,0,1] neg_lo:[0,1,0] neg_hi:[0,1,0]
	v_add_u32_e32 v6, 0x1e00, v6
	ds_read_b128 v[10:13], v7 offset:64
	v_mov_b32_e32 v7, v23
	s_nop 1
	v_mov_b32_dpp v20, v7 quad_perm:[2,2,2,2] row_mask:0xf bank_mask:0xf
	s_waitcnt lgkmcnt(2)
	v_pk_fma_f32 v[102:103], v[106:107], v[20:21], v[8:9] op_sel_hi:[1,0,1] neg_lo:[0,1,0] neg_hi:[0,1,0]
	v_pk_fma_f32 v[22:23], v[108:109], v[20:21], v[22:23] op_sel_hi:[1,0,1] neg_lo:[0,1,0] neg_hi:[0,1,0]
	v_mov_b32_e32 v24, v102
	v_mov_b32_e32 v20, v131
	ds_read_b128 v[6:9], v6 offset:64
	s_nop 1
	v_mov_b32_dpp v20, v24 quad_perm:[3,3,3,3] row_mask:0xf bank_mask:0xf
	s_waitcnt lgkmcnt(2)
	v_pk_fma_f32 v[100:101], v[100:101], v[20:21], v[22:23] op_sel_hi:[1,0,1] neg_lo:[0,1,0] neg_hi:[0,1,0]
	v_pk_fma_f32 v[22:23], v[98:99], v[20:21], v[102:103] op_sel_hi:[1,0,1] neg_lo:[0,1,0] neg_hi:[0,1,0]
	v_mov_b32_e32 v24, v131
	v_mov_b32_e32 v20, v23
	v_lshlrev_b32_e32 v98, 5, v33
	v_lshl_add_u32 v33, v15, 2, s6
	v_mov_b32_dpp v24, v20 quad_perm:[3,3,3,3] row_mask:0xf bank_mask:0xf
	v_and_b32_e32 v20, -4, v1
	s_waitcnt lgkmcnt(1)
	v_pk_fma_f32 v[12:13], v[12:13], v[24:25], v[100:101] op_sel_hi:[1,0,1] neg_lo:[0,1,0] neg_hi:[0,1,0]
	v_add_u32_e32 v20, 0, v20
	v_mov_b32_e32 v93, v12
	s_waitcnt vmcnt(0)
	v_add_u32_e32 v97, 0x24a00, v20
	v_add_u32_e32 v20, 0x24b00, v20
	ds_read_b32 v97, v97
	ds_read_b32 v99, v20
	v_mov_b32_e32 v20, 0
	s_waitcnt lgkmcnt(1)
	v_mul_f32_e32 v100, v2, v97
	v_mov_b32_dpp v20, v93 quad_perm:[3,3,3,3] row_mask:0xf bank_mask:0xf
	s_waitcnt lgkmcnt(0)
	v_mul_f32_e32 v93, v97, v99
	v_or_b32_e32 v99, v32, v98
	v_cvt_pk_bf16_f32 v102, v100, s0
	v_mad_u64_u32 v[100:101], s[6:7], v99, s8, v[14:15]
	v_lshl_add_u32 v99, v100, 1, 0
	v_add_u32_e32 v100, 0x18000, v99
	ds_write_b16 v100, v102
	v_mul_f32_e32 v100, v2, v93
	v_cvt_pk_bf16_f32 v100, v100, s0
	v_add_u32_e32 v99, 0x1a400, v99
	ds_write_b16 v99, v100
	s_and_saveexec_b64 s[28:29], vcc
	s_cbranch_execz .LBB0_219
	v_mad_u32_u24 v99, v32, s8, v14
	v_lshl_add_u32 v99, v99, 1, 0
	s_movk_i32 s6, 0x90
	v_add_u32_e32 v100, 0x18000, v99
	v_add_u32_e32 v99, 0x1a400, v99
	v_mad_u32_u24 v32, v32, s6, v33
	ds_write_b16 v100, v131
	ds_write_b16 v99, v131
	ds_write_b32 v32, v2

.LBB0_235:
	s_or_b64 exec, exec, s[28:29]
	v_mov_b32_e32 v101, v88
	v_mov_b32_e32 v102, v89
	v_mov_b32_e32 v103, v91
	v_mov_b32_e32 v104, v90
	s_setprio 0
